# NSA: first K/V tile of each following sequence prefetched early (CMP2 tile in the unit prologue, selected-branch tile 0 before the top-k step, window tile before the selected-branch epilogue), no vmcn
# speedup vs baseline: 1.0107x; 1.0024x over previous
; template <bool HASP, bool HASV>
; __device__ __forceinline__ void stage_load(Stage& st, const bf16_t* Kg, size_t ldk, const bf16_t* Pg, const bf16_t* Vg, size_t ldv, int tid) {
;     const int r0 = tid >> 4, c0 = (tid & 15) * 8;
;     st.k0 = *(const u32x4*)(Kg + (size_t)r0 * ldk + c0); st.k1 = *(const u32x4*)(Kg + (size_t)(r0 + 32) * ldk + c0);
;     if (HASP) st.kp = *(const u32x4*)(Pg + (size_t)(tid >> 3) * 64 + (tid & 7) * 8);
;     if (HASV) { st.v0 = *(const u32x4*)(Vg + (size_t)r0 * ldv + c0); st.v1 = *(const u32x4*)(Vg + (size_t)(r0 + 32) * ldv + c0); }
; }
; __device__ __forceinline__ void nsa_unit(Frame& F, int b, int g, int c) {
;     ...
;     int tid = F.tid; asm volatile("" : "+v"(tid));
;     const int lane = tid & 63, w = __builtin_amdgcn_readfirstlane(tid >> 6), ql = lane & 31, hi = lane >> 5, head = ql & 3, tokl = 8 * w + (ql >> 2);
;     const int ts = 64 * c + tokl; const size_t trow = (size_t)b * S + ts; const int hg = g * 4 + head;
;     const float C = 0.08838834764831845f * LOG2E;
;     const bf16_t* KV = (const bf16_t*)(ws + WS_KVNSA) + (size_t)b * S * 3072 + g * 128;
;     bf16_t* accb = (bf16_t*)(ws + WS_NSAACC) + trow * 2048 + hg * 128;
;     bf16x8 qf[8];
;     { const bf16_t* qrow = (const bf16_t*)(ws + WS_QNSA) + trow * 2048 + hg * 128 + 8 * hi;
; #pragma unroll
;       for (int d = 0; d < 8; ++d) qf[d] = *(const bf16x8*)(qrow + 16 * d); }
;     const float* gp = (const float*)(ws + WS_GATES) + trow * 48 + hg * 3; const float gc = gp[0], gs = gp[1], gw = gp[2];
;     f32x16 O[4]; float m, l;
;     {
;         const bf16_t* KC = (const bf16_t*)(ws + WS_KC) + (size_t)(b * 4 + g) * 256 * 128; const bf16_t* VC = (const bf16_t*)(ws + WS_VC) + (size_t)(b * 4 + g) * 256 * 128;
;         const int nct = (4 * c + 2) / 64 + 1, limc = (ts - 31) >> 4;
;         m = -1e30f; l = 0.f; zero_o(O);
;         run_seq<M_CMP1, 8>(lds, tid, qf, O, m, l, C, KC, 128, KC, VC, 128, 0, nct - 1, 0ull, limc, -1, 0ull, 0, 0.f, tokl, head);
.LBB0_840:
	s_xor_b64 s[96:97], s[0:1], -1
	s_and_b64 s[0:1], s[0:1], exec
	v_mov_b32_e32 v56, v0
	s_cselect_b32 s68, s81, s80
	v_readfirstlane_b32 s0, v56
	s_ashr_i32 s73, s0, 6
	s_lshl_b32 s74, s73, 3
	v_bfe_u32 v210, v56, 2, 3
	v_or_b32_e32 v167, s74, v210
	v_lshl_add_u32 v154, s68, 6, v167
	v_ashrrev_i32_e32 v155, 31, v154
	v_and_b32_e32 v43, 3, v56
	v_lshl_add_u64 v[156:157], s[84:85], 0, v[154:155]
	v_readlane_b32 s0, v245, 63
	v_or_b32_e32 v149, s64, v43
	v_lshlrev_b64 v[2:3], 12, v[156:157]
	v_readlane_b32 s1, v244, 0
	v_bfe_u32 v159, v56, 5, 1
	v_lshlrev_b32_e32 v150, 8, v149
	v_lshl_add_u64 v[2:3], s[0:1], 0, v[2:3]
	v_lshl_add_u64 v[2:3], v[2:3], 0, v[150:151]
	v_lshlrev_b32_e32 v150, 4, v159
	v_lshl_add_u64 v[2:3], v[2:3], 0, v[150:151]
	s_movk_i32 s2, 0xc0
	global_load_dwordx4 v[98:101], v[2:3], off
	global_load_dwordx4 v[102:105], v[2:3], off offset:32
	global_load_dwordx4 v[106:109], v[2:3], off offset:64
	global_load_dwordx4 v[110:113], v[2:3], off offset:96
	global_load_dwordx4 v[114:117], v[2:3], off offset:128
	global_load_dwordx4 v[118:121], v[2:3], off offset:160
	global_load_dwordx4 v[122:125], v[2:3], off offset:192
	global_load_dwordx4 v[126:129], v[2:3], off offset:224
	v_mad_u64_u32 v[2:3], s[0:1], v156, s2, v[152:153]
	v_mul_u32_u24_e32 v4, 3, v149
	v_mad_i32_i24 v3, v157, s2, v3
	v_lshlrev_b32_e32 v4, 2, v4
	s_waitcnt lgkmcnt(0)
	v_mov_b32_e32 v5, v151
	v_lshl_add_u64 v[2:3], v[2:3], 0, v[4:5]
	global_load_dwordx3 v[146:148], v[2:3], off
	v_and_b32_e32 v2, 31, v56
	v_mul_u32_u24_e32 v2, 0x190, v2
	v_ashrrev_i32_e32 v162, 4, v56
	v_add3_u32 v155, 0, v2, v150
	v_lshlrev_b32_e32 v2, 3, v56
	v_ashrrev_i32_e32 v163, 31, v162
	v_add_u32_e32 v164, 32, v162
	v_and_b32_e32 v42, 0x78, v2
	v_lshlrev_b64 v[44:45], 8, v[162:163]
	v_ashrrev_i32_e32 v165, 31, v164
	v_lshl_add_u64 v[2:3], s[86:87], 0, v[44:45]
	v_lshlrev_b32_e32 v150, 1, v42
	v_lshlrev_b64 v[48:49], 8, v[164:165]
	v_lshl_add_u64 v[50:51], v[2:3], 0, v[150:151]
	v_lshl_add_u64 v[2:3], s[86:87], 0, v[48:49]
	v_lshl_add_u64 v[52:53], v[2:3], 0, v[150:151]
	global_load_dwordx4 v[34:37], v[50:51], off
	global_load_dwordx4 v[38:41], v[52:53], off
	global_load_dwordx4 v[130:133], v[50:51], off
	global_load_dwordx4 v[134:137], v[52:53], off
	v_lshl_add_u64 v[144:145], s[88:89], 0, v[44:45]
	v_lshl_add_u64 v[144:145], v[144:145], 0, v[150:151]
	global_load_dwordx4 v[138:141], v[144:145], off
	v_lshl_add_u64 v[144:145], s[88:89], 0, v[48:49]
	v_lshl_add_u64 v[144:145], v[144:145], 0, v[150:151]
	global_load_dwordx4 v[142:145], v[144:145], off
	s_barrier
	v_subrev_u32_e32 v2, 31, v154
	v_ashrrev_i32_e32 v2, 4, v2
	v_lshlrev_b32_e32 v158, 2, v159
	v_lshlrev_b32_e32 v3, 4, v56
	v_sub_u32_e32 v172, v2, v158
	v_and_b32_e32 v2, 15, v56
	s_lshr_b32 s82, s68, 4
	v_and_b32_e32 v165, 0xf0, v3
	v_mul_lo_u32 v187, v162, s42
	v_lshl_or_b32 v46, v2, 4, v44
	v_mov_b32_e32 v47, v45
	v_and_b32_e32 v163, 63, v56
	v_lshlrev_b64 v[160:161], 11, v[156:157]
	v_lshlrev_b32_e32 v166, 7, v149
	v_add3_u32 v57, 0, v187, v165
	s_add_i32 s72, s82, 1
	v_lshl_add_u64 v[54:55], s[94:95], 0, v[46:47]
	s_mov_b64 s[66:67], 0
	s_mov_b32 s83, 0
	v_mov_b32_e32 v59, 0
	v_mov_b32_e32 v60, 0xf149f2ca
	v_mov_b32_e32 v58, v172

; template <int MODE, int NQ> ...
;     ...
;     int j; unsigned long long rem = 0ull;
;     if (MODE == M_SEL) { rem = tmask; j = rem ? (int)__builtin_ctzll(rem) : -1; rem &= rem - 1ull; } else { j = jlo <= jhi ? jlo : -1; }
;     Stage st;
;     __syncthreads();
;     if (j >= 0) stage_load<HASP, HASV>(st, Kg + (size_t)j * 64 * ldk, ldk, Pg + (size_t)j * 64 * 64, Vg + (size_t)j * 64 * ldv, ldv, tid);
; __device__ __forceinline__ void nsa_unit(Frame& F, int b, int g, int c) {
;     ...
;         const float inv_l = l > 0.f ? 1.0f / l : 0.f;
;         run_seq<M_CMP2, 8>(lds, tid, qf, O, m, l, C, KC, 128, KC, VC, 128, 0, nct - 1, 0ull, limc, -1, 0ull, 0, inv_l, tokl, head);
.LBB0_845:
	v_div_scale_f32 v4, s[0:1], v3, v3, 1.0
	v_rcp_f32_e32 v5, v4
	v_lshrrev_b32_e32 v6, 2, v56
	v_lshlrev_b32_e32 v150, 1, v42
	v_fma_f32 v7, -v4, v5, 1.0
	v_fmac_f32_e32 v5, v7, v5
	v_div_scale_f32 v7, vcc, 1.0, v3, 1.0
	v_mul_f32_e32 v8, v7, v5
	v_fma_f32 v9, -v4, v8, v7
	v_fmac_f32_e32 v8, v9, v5
	v_fma_f32 v4, -v4, v8, v7
	v_div_fmas_f32 v4, v4, v5, v8
	v_div_fixup_f32 v4, v4, v3, 1.0
	v_cmp_lt_f32_e32 vcc, 0, v3
	v_lshlrev_b32_e32 v5, 2, v56
	v_and_or_b32 v3, v6, 3, v158
	v_cndmask_b32_e32 v168, 0, v4, vcc
	v_and_b32_e32 v4, 16, v56
	v_and_or_b32 v4, v5, 12, v4
	v_mul_u32_u24_e32 v3, 0x140, v3
	v_lshlrev_b32_e32 v4, 1, v4
	v_add3_u32 v206, 0, v3, v4
	v_lshl_add_u64 v[4:5], s[88:89], 0, v[44:45]
	v_lshl_add_u64 v[4:5], v[4:5], 0, v[150:151]
	v_lshl_add_u64 v[6:7], s[88:89], 0, v[48:49]
	s_barrier
	v_lshl_add_u64 v[6:7], v[6:7], 0, v[150:151]
	s_movk_i32 s0, 0x140
	v_mul_lo_u32 v208, v162, s0
	s_lshl_b32 s0, s68, 10
	s_lshl_b32 s38, s73, 9
	v_lshlrev_b32_e32 v3, 6, v210
	v_mov_b32_e32 v2, 0
	s_movk_i32 s42, 0x190
	s_and_b32 s0, s0, 0xc000
	v_or3_b32 v3, s38, v3, v159
	v_mul_lo_u32 v207, v164, s42
	v_add_u32_e32 v209, 0x2800, v208
	s_mov_b32 s39, 0
	v_cmp_eq_u32_e64 s[2:3], 0, v43
	v_mov_b32_e32 v169, v168
	s_add_u32 s40, s0, 0x4000
	v_lshl_add_u32 v174, v3, 2, s78
	v_lshl_add_u64 v[170:171], s[70:71], 0, v[46:47]
	v_or_b32_e32 v175, 14, v159
	s_mov_b64 s[36:37], 0
	v_mov_b32_e32 v3, v2
	v_mov_b32_e32 v4, v2
	v_mov_b32_e32 v5, v2
	v_mov_b32_e32 v6, v2
	v_mov_b32_e32 v7, v2
	v_mov_b32_e32 v8, v2
	v_mov_b32_e32 v9, v2
	v_mov_b32_e32 v10, v2
	v_mov_b32_e32 v11, v2
	v_mov_b32_e32 v12, v2
	v_mov_b32_e32 v13, v2
	v_mov_b32_e32 v14, v2
	v_mov_b32_e32 v15, v2
	v_mov_b32_e32 v16, v2
	v_mov_b32_e32 v17, v2
	v_mov_b32_e32 v18, v2
	v_mov_b32_e32 v19, v2
	v_mov_b32_e32 v20, v2
	v_mov_b32_e32 v21, v2
	v_mov_b32_e32 v22, v2
	v_mov_b32_e32 v23, v2
	v_mov_b32_e32 v24, v2
	v_mov_b32_e32 v25, v2
	v_mov_b32_e32 v26, v2
	v_mov_b32_e32 v27, v2
	v_mov_b32_e32 v28, v2
	v_mov_b32_e32 v29, v2
	v_mov_b32_e32 v30, v2
	v_mov_b32_e32 v31, v2
	v_mov_b32_e32 v32, v2
	v_mov_b32_e32 v33, v2
	s_waitcnt vmcnt(5)
	v_mov_b32_e32 v34, v2
	v_mov_b32_e32 v35, v2
	v_mov_b32_e32 v36, v2
	v_mov_b32_e32 v37, v2
	s_waitcnt vmcnt(4)
	v_mov_b32_e32 v38, v2
	v_mov_b32_e32 v39, v2
	v_mov_b32_e32 v40, v2
	v_mov_b32_e32 v41, v2
	v_mov_b32_e32 v42, v2
	v_mov_b32_e32 v43, v2
	v_mov_b32_e32 v44, v2
	v_mov_b32_e32 v45, v2
	v_mov_b32_e32 v46, v2
	v_mov_b32_e32 v47, v2
	v_mov_b32_e32 v48, v2
	v_mov_b32_e32 v49, v2
	v_mov_b32_e32 v50, v2
	v_mov_b32_e32 v51, v2
	v_mov_b32_e32 v52, v2
	v_mov_b32_e32 v53, v2
	v_mov_b32_e32 v54, v2
	v_mov_b32_e32 v55, v2
	v_mov_b32_e32 v56, v2
	v_mov_b32_e32 v57, v2
	v_mov_b32_e32 v58, v2
	v_mov_b32_e32 v59, v2
	v_mov_b32_e32 v60, v2
	v_mov_b32_e32 v61, v2
	v_mov_b32_e32 v62, v2
	v_mov_b32_e32 v63, v2
	v_mov_b32_e32 v64, v2
	v_mov_b32_e32 v65, v2
	s_branch .LBB0_847

; __device__ __forceinline__ u32x2 pack4(f32x4 v) { u32x2 w; w.x = cvtpk(v[0], v[1]); w.y = cvtpk(v[2], v[3]); return w; }
; template <bool HASP, bool HASV>
; __device__ __forceinline__ void stage_load(Stage& st, const bf16_t* Kg, size_t ldk, const bf16_t* Pg, const bf16_t* Vg, size_t ldv, int tid) {
;     const int r0 = tid >> 4, c0 = (tid & 15) * 8;
;     st.k0 = *(const u32x4*)(Kg + (size_t)r0 * ldk + c0); st.k1 = *(const u32x4*)(Kg + (size_t)(r0 + 32) * ldk + c0);
;     if (HASP) st.kp = *(const u32x4*)(Pg + (size_t)(tid >> 3) * 64 + (tid & 7) * 8);
;     if (HASV) { st.v0 = *(const u32x4*)(Vg + (size_t)r0 * ldv + c0); st.v1 = *(const u32x4*)(Vg + (size_t)(r0 + 32) * ldv + c0); }
; }
; __device__ __forceinline__ void nsa_unit(Frame& F, int b, int g, int c) {
;     ...
; #pragma unroll
;         for (int db = 0; db < 4; ++db)
; #pragma unroll
;             for (int q4 = 0; q4 < 4; ++q4) { f32x4 o = {O[db][4 * q4], O[db][4 * q4 + 1], O[db][4 * q4 + 2], O[db][4 * q4 + 3]}; *(u32x2*)(accb + 32 * db + 8 * q4 + 4 * hi) = pack4(o * gc); }
.LBB0_866:
	s_mov_b32 s98, s65
	s_mov_b32 s99, s69
	v_mad_i64_i32 v[142:143], s[100:101], v162, s33, 0
	v_lshl_add_u64 v[142:143], v[142:143], 1, s[98:99]
	v_lshl_add_u64 v[142:143], v[142:143], 0, v[150:151]
	global_load_dwordx4 v[130:133], v[142:143], off offset:2048
	global_load_dwordx4 v[134:137], v[142:143], off offset:3072
	v_mad_i64_i32 v[142:143], s[100:101], v164, s33, 0
	v_lshl_add_u64 v[142:143], v[142:143], 1, s[98:99]
	v_lshl_add_u64 v[142:143], v[142:143], 0, v[150:151]
	global_load_dwordx4 v[138:141], v[142:143], off offset:2048
	global_load_dwordx4 v[142:145], v[142:143], off offset:3072
	v_readlane_b32 s0, v244, 1
	v_readlane_b32 s1, v244, 2
	v_lshlrev_b32_e32 v68, 1, v166
	v_mov_b32_e32 v69, v151
	v_lshl_add_u64 v[66:67], v[160:161], 1, s[0:1]
	v_lshl_add_u64 v[66:67], v[66:67], 0, v[68:69]
	v_lshlrev_b32_e32 v68, 3, v159
	v_pk_mul_f32 v[52:53], v[146:147], v[52:53] op_sel_hi:[0,1]
	v_pk_mul_f32 v[50:51], v[146:147], v[50:51] op_sel_hi:[0,1]
	v_pk_mul_f32 v[36:37], v[146:147], v[36:37] op_sel_hi:[0,1]
	v_pk_mul_f32 v[34:35], v[146:147], v[34:35] op_sel_hi:[0,1]
	v_pk_mul_f32 v[20:21], v[146:147], v[20:21] op_sel_hi:[0,1]
	v_pk_mul_f32 v[18:19], v[146:147], v[18:19] op_sel_hi:[0,1]
	v_pk_mul_f32 v[4:5], v[146:147], v[4:5] op_sel_hi:[0,1]
	v_pk_mul_f32 v[2:3], v[146:147], v[2:3] op_sel_hi:[0,1]
	s_cmp_gt_u32 s68, 15
	v_lshl_add_u64 v[160:161], v[66:67], 0, v[68:69]
	v_cvt_pk_bf16_f32 v220, v50, v51
	v_cvt_pk_bf16_f32 v221, v52, v53
	v_cvt_pk_bf16_f32 v228, v34, v35
	v_cvt_pk_bf16_f32 v229, v36, v37
	v_cvt_pk_bf16_f32 v236, v18, v19
	v_cvt_pk_bf16_f32 v237, v20, v21
	v_cvt_pk_bf16_f32 v246, v2, v3
	v_cvt_pk_bf16_f32 v247, v4, v5
	s_cselect_b64 s[6:7], -1, 0
	s_lshl_b64 s[0:1], 2, s68
	v_pk_mul_f32 v[50:51], v[146:147], v[56:57] op_sel_hi:[0,1]
	v_pk_mul_f32 v[52:53], v[146:147], v[54:55] op_sel_hi:[0,1]
	v_pk_mul_f32 v[34:35], v[146:147], v[40:41] op_sel_hi:[0,1]
	v_pk_mul_f32 v[36:37], v[146:147], v[38:39] op_sel_hi:[0,1]
	v_pk_mul_f32 v[18:19], v[146:147], v[24:25] op_sel_hi:[0,1]
	v_pk_mul_f32 v[20:21], v[146:147], v[22:23] op_sel_hi:[0,1]
	v_pk_mul_f32 v[2:3], v[146:147], v[8:9] op_sel_hi:[0,1]
	v_pk_mul_f32 v[4:5], v[146:147], v[6:7] op_sel_hi:[0,1]
	s_add_u32 s26, s0, -1
	v_cvt_pk_bf16_f32 v222, v52, v53
	v_cvt_pk_bf16_f32 v223, v50, v51
	v_cvt_pk_bf16_f32 v230, v36, v37
	v_cvt_pk_bf16_f32 v231, v34, v35
	v_cvt_pk_bf16_f32 v238, v20, v21
	v_cvt_pk_bf16_f32 v239, v18, v19
	v_cvt_pk_bf16_f32 v248, v4, v5
	v_cvt_pk_bf16_f32 v249, v2, v3
	s_addc_u32 s27, s1, -1
	s_add_i32 s0, s68, -2
	v_pk_mul_f32 v[50:51], v[146:147], v[60:61] op_sel_hi:[0,1]
	v_pk_mul_f32 v[52:53], v[146:147], v[58:59] op_sel_hi:[0,1]
	v_pk_mul_f32 v[34:35], v[146:147], v[44:45] op_sel_hi:[0,1]
	v_pk_mul_f32 v[36:37], v[146:147], v[42:43] op_sel_hi:[0,1]
	v_pk_mul_f32 v[18:19], v[146:147], v[28:29] op_sel_hi:[0,1]
	v_pk_mul_f32 v[20:21], v[146:147], v[26:27] op_sel_hi:[0,1]
	v_pk_mul_f32 v[2:3], v[146:147], v[12:13] op_sel_hi:[0,1]
	v_pk_mul_f32 v[4:5], v[146:147], v[10:11] op_sel_hi:[0,1]
	v_cmp_ne_u32_e32 vcc, 0, v163
	v_cmp_ge_i32_e64 s[0:1], s0, v163
	s_add_i32 s2, s68, -1
	v_cvt_pk_bf16_f32 v224, v52, v53
	v_cvt_pk_bf16_f32 v225, v50, v51
	v_cvt_pk_bf16_f32 v232, v36, v37
	v_cvt_pk_bf16_f32 v233, v34, v35
	v_cvt_pk_bf16_f32 v240, v20, v21
	v_cvt_pk_bf16_f32 v241, v18, v19
	v_cvt_pk_bf16_f32 v250, v4, v5
	v_cvt_pk_bf16_f32 v251, v2, v3
	s_and_b64 s[8:9], vcc, s[0:1]
	s_lshl_b64 s[0:1], 1, s68
	s_lshl_b64 s[2:3], 1, s2
	v_pk_mul_f32 v[50:51], v[146:147], v[64:65] op_sel_hi:[0,1]
	v_pk_mul_f32 v[52:53], v[146:147], v[62:63] op_sel_hi:[0,1]
	v_pk_mul_f32 v[34:35], v[146:147], v[48:49] op_sel_hi:[0,1]
	v_pk_mul_f32 v[36:37], v[146:147], v[46:47] op_sel_hi:[0,1]
	v_pk_mul_f32 v[18:19], v[146:147], v[32:33] op_sel_hi:[0,1]
	v_pk_mul_f32 v[20:21], v[146:147], v[30:31] op_sel_hi:[0,1]
	v_pk_mul_f32 v[2:3], v[146:147], v[16:17] op_sel_hi:[0,1]
	v_pk_mul_f32 v[4:5], v[146:147], v[14:15] op_sel_hi:[0,1]
	s_mov_b32 s12, s26
	s_mov_b32 s13, s27
	s_or_b64 s[10:11], s[2:3], s[0:1]
	v_cvt_pk_bf16_f32 v226, v52, v53
	v_cvt_pk_bf16_f32 v227, v50, v51
	v_cvt_pk_bf16_f32 v234, v36, v37
	v_cvt_pk_bf16_f32 v235, v34, v35
	v_cvt_pk_bf16_f32 v242, v20, v21
	v_cvt_pk_bf16_f32 v243, v18, v19
	v_cvt_pk_bf16_f32 v252, v4, v5
	v_cvt_pk_bf16_f32 v253, v2, v3
	s_cmp_lt_u32 s68, 16
	s_mov_b64 s[14:15], s[12:13]
	s_barrier
	s_cbranch_scc1 .LBB0_872
	v_mov_b32_e32 v2, 0xff800000
	s_and_saveexec_b64 s[0:1], s[8:9]
	s_cbranch_execz .LBB0_869
	v_or_b32_e32 v2, s38, v163
	v_lshl_add_u32 v2, v2, 2, 0
	v_add_u32_e32 v3, 0x16800, v2
	v_add_u32_e32 v2, 0x1a800, v2
	ds_read_b32 v3, v3
	ds_read_b32 v2, v2
	s_waitcnt lgkmcnt(0)
	v_add_f32_e32 v2, v3, v2

; #define LAS __attribute__((address_space(3)))
; __device__ __forceinline__ void nsa_unit(Frame& F, int b, int g, int c) {
;     ...
;         if (lane == 0) uni[w] = wuni;
;     }
;     __syncthreads();
;     unsigned long long mymask, tmask = 0ull;
;     { const LAS unsigned long long* selm = (const LAS unsigned long long*)(lds + OFF_SELM); const LAS unsigned long long* uni = (const LAS unsigned long long*)(lds + OFF_UNI);
;       mymask = selm[tokl];
; #pragma unroll
;       for (int i = 0; i < 8; ++i) tmask |= uni[i];
;       tmask &= (2ull << c) - 1ull;
;       tmask = ((unsigned long long)(unsigned)__builtin_amdgcn_readfirstlane((int)(unsigned)(tmask >> 32)) << 32) | (unsigned long long)(unsigned)__builtin_amdgcn_readfirstlane((int)(unsigned)tmask); }
;     m = -1e30f; l = 0.f; zero_o(O);
;     run_seq<M_SEL, 8>(lds, tid, qf, O, m, l, C, KV + 2 * 512, 3072, KV, KV + 3 * 512, 3072, 0, c, tmask, ts, -1, mymask, 0, 0.f, tokl, head);
.LBB0_919:
	s_or_b64 exec, exec, s[0:1]
	v_lshl_add_u32 v6, v167, 3, 0
	s_add_i32 s0, 0, 0x1ea00
	v_mov_b32_e32 v2, s0
	v_add_u32_e32 v6, 0x1e800, v6
	s_waitcnt lgkmcnt(0)
	s_barrier
	ds_read_b128 v[2:5], v2
	ds_read_b64 v[170:171], v6
	v_mov_b32_e32 v6, s77
	ds_read_b128 v[6:9], v6
	s_waitcnt lgkmcnt(2)
	v_or_b32_e32 v10, v4, v2
	v_mov_b32_e32 v2, s75
	v_or_b32_e32 v11, v5, v3
	ds_read_b128 v[2:5], v2
	s_waitcnt lgkmcnt(1)
	v_or_b32_e32 v6, v10, v6
	v_or_b32_e32 v7, v11, v7
	v_or_b32_e32 v10, v6, v8
	v_mov_b32_e32 v6, s79
	v_or_b32_e32 v11, v7, v9
	ds_read_b128 v[6:9], v6
	s_waitcnt lgkmcnt(1)
	v_or_b32_e32 v2, v10, v2
	v_or_b32_e32 v3, v11, v3
	v_or_b32_e32 v2, v2, v4
	v_or_b32_e32 v3, v3, v5
	s_waitcnt lgkmcnt(0)
	v_or_b32_e32 v2, v2, v6
	v_or_b32_e32 v3, v3, v7
	v_or_b32_e32 v2, v2, v8
	v_or_b32_e32 v3, v3, v9
	v_and_b32_e32 v2, s26, v2
	v_and_b32_e32 v3, s27, v3
	v_readfirstlane_b32 s2, v2
	v_readfirstlane_b32 s3, v3
	s_cmp_lg_u64 s[2:3], 0
	s_barrier
	s_cbranch_scc0 .LBB0_956
	s_add_u32 s0, s2, -1
	s_addc_u32 s1, s3, -1
	s_ff1_i32_b64 s8, s[2:3]
	s_and_b64 s[0:1], s[0:1], s[2:3]
	s_mul_i32 s2, s8, 0x60000
	s_add_u32 s2, s65, s2
	s_addc_u32 s3, s69, 0
	v_mad_i64_i32 v[166:167], s[4:5], v162, s33, 0
	v_lshl_add_u64 v[2:3], v[166:167], 1, s[2:3]
	v_mad_i64_i32 v[168:169], s[4:5], v164, s33, 0
	v_lshl_add_u64 v[2:3], v[2:3], 0, v[150:151]
	v_lshl_add_u64 v[4:5], v[168:169], 1, s[2:3]
	v_lshl_add_u64 v[4:5], v[4:5], 0, v[150:151]
	s_cmp_eq_u32 s8, 0
	s_cbranch_scc1 .Lsel_pf_ok
	s_waitcnt vmcnt(0)
	global_load_dwordx4 v[130:133], v[2:3], off offset:2048
	global_load_dwordx4 v[134:137], v[2:3], off offset:3072
	global_load_dwordx4 v[138:141], v[4:5], off offset:2048
	global_load_dwordx4 v[142:145], v[4:5], off offset:3072
.Lsel_pf_ok:
	v_mov_b32_e32 v16, v151
	v_mov_b32_e32 v17, v151
	v_mov_b32_e32 v2, v151
	v_mov_b32_e32 v3, v151
	v_mov_b32_e32 v4, v151
	v_mov_b32_e32 v5, v151
	v_mov_b32_e32 v6, v151
	v_mov_b32_e32 v7, v151
	v_mov_b32_e32 v8, v151
	v_mov_b32_e32 v9, v151
	v_mov_b32_e32 v10, v151
	v_mov_b32_e32 v11, v151
	v_mov_b32_e32 v12, v151
	v_mov_b32_e32 v13, v151
	v_mov_b32_e32 v14, v151
	v_mov_b32_e32 v15, v151
	v_mov_b32_e32 v146, 0
	v_mov_b64_e32 v[32:33], v[16:17]
	v_mov_b64_e32 v[48:49], v[16:17]
	v_mov_b64_e32 v[64:65], v[16:17]
	s_mov_b32 s5, 0
	v_mov_b32_e32 v211, 0xf149f2ca
	v_mov_b64_e32 v[30:31], v[14:15]
	v_mov_b64_e32 v[28:29], v[12:13]
	v_mov_b64_e32 v[26:27], v[10:11]
	v_mov_b64_e32 v[24:25], v[8:9]
	v_mov_b64_e32 v[22:23], v[6:7]
	v_mov_b64_e32 v[20:21], v[4:5]
	v_mov_b64_e32 v[18:19], v[2:3]
	v_mov_b64_e32 v[46:47], v[14:15]
	v_mov_b64_e32 v[44:45], v[12:13]
	v_mov_b64_e32 v[42:43], v[10:11]
	v_mov_b64_e32 v[40:41], v[8:9]
	v_mov_b64_e32 v[38:39], v[6:7]
	v_mov_b64_e32 v[36:37], v[4:5]
	v_mov_b64_e32 v[34:35], v[2:3]
	v_mov_b64_e32 v[62:63], v[14:15]
	v_mov_b64_e32 v[60:61], v[12:13]
	v_mov_b64_e32 v[58:59], v[10:11]
	v_mov_b64_e32 v[56:57], v[8:9]
	v_mov_b64_e32 v[54:55], v[6:7]
	v_mov_b64_e32 v[52:53], v[4:5]
	v_mov_b64_e32 v[50:51], v[2:3]
	v_mov_b32_e32 v78, 0
	v_mov_b32_e32 v79, v146
	v_mov_b32_e32 v80, 0
	v_mov_b32_e32 v81, v146
	v_mov_b32_e32 v74, 0
	v_mov_b32_e32 v75, v146
	v_mov_b32_e32 v76, 0
	v_mov_b32_e32 v77, v146
	v_mov_b32_e32 v70, 0
	v_mov_b32_e32 v71, v146
	v_mov_b32_e32 v72, 0
	v_mov_b32_e32 v73, v146
	v_mov_b32_e32 v66, 0
	v_mov_b32_e32 v67, v146
	v_mov_b32_e32 v68, 0
	v_mov_b32_e32 v69, v146
	v_mov_b32_e32 v94, 0
	v_mov_b32_e32 v95, v146
	v_mov_b32_e32 v96, 0
	v_mov_b32_e32 v97, v146
	v_mov_b32_e32 v90, 0
	v_mov_b32_e32 v91, v146
	v_mov_b32_e32 v92, 0
	v_mov_b32_e32 v93, v146
	v_mov_b32_e32 v86, 0
	v_mov_b32_e32 v87, v146
	v_mov_b32_e32 v88, 0
	v_mov_b32_e32 v89, v146
	v_mov_b32_e32 v82, 0
	v_mov_b32_e32 v83, v146
	v_mov_b32_e32 v84, 0
	v_mov_b32_e32 v85, v146
	v_mov_b32_e32 v190, 0
	v_mov_b32_e32 v191, v146
	v_mov_b32_e32 v192, 0
	v_mov_b32_e32 v193, v146
	v_mov_b32_e32 v180, 0
	v_mov_b32_e32 v181, v146
	v_mov_b32_e32 v182, 0
	v_mov_b32_e32 v183, v146
	v_mov_b32_e32 v176, 0
	v_mov_b32_e32 v177, v146
	v_mov_b32_e32 v178, 0
	v_mov_b32_e32 v179, v146
	v_mov_b32_e32 v172, 0
	v_mov_b32_e32 v173, v146
	v_mov_b32_e32 v174, 0
	v_mov_b32_e32 v175, v146
	v_mov_b32_e32 v202, 0
	v_mov_b32_e32 v203, v146
	v_mov_b32_e32 v204, 0
	v_mov_b32_e32 v205, v146
	v_mov_b32_e32 v198, 0
	v_mov_b32_e32 v199, v146
	v_mov_b32_e32 v200, 0
	v_mov_b32_e32 v201, v146
	v_mov_b32_e32 v194, 0
	v_mov_b32_e32 v195, v146
	v_mov_b32_e32 v196, 0
	v_mov_b32_e32 v197, v146
	v_mov_b32_e32 v184, 0
	v_mov_b32_e32 v185, v146
	v_mov_b32_e32 v188, 0
	v_mov_b32_e32 v189, v146

; __device__ __forceinline__ u32x2 pack4(f32x4 v) { u32x2 w; w.x = cvtpk(v[0], v[1]); w.y = cvtpk(v[2], v[3]); return w; }
; __device__ __forceinline__ void nsa_unit(Frame& F, int b, int g, int c) {
;     ...
;     { const float sc = l > 0.f ? gs / l : 0.f;
; #pragma unroll
;       for (int db = 0; db < 4; ++db)
; #pragma unroll
;           for (int q4 = 0; q4 < 4; ++q4) { bf16_t* p = accb + 32 * db + 8 * q4 + 4 * hi; f32x4 o = {O[db][4 * q4], O[db][4 * q4 + 1], O[db][4 * q4 + 2], O[db][4 * q4 + 3]}; const u32x2 w = *(const u32x2*)p;
;               const f32x4 pr = {__uint_as_float(w.x << 16), __uint_as_float(w.x & 0xffff0000u), __uint_as_float(w.y << 16), __uint_as_float(w.y & 0xffff0000u)}; *(u32x2*)p = pack4(pr + o * sc); } }
;     m = -1e30f; l = 0.f; zero_o(O);
;     run_seq<M_WIN, 8>(lds, tid, qf, O, m, l, C, KV + 4 * 512, 3072, KV, KV + 5 * 512, 3072, c >= 8 ? c - 8 : 0, c, 0ull, ts, ts - 512, 0ull, 0, 0.f, tokl, head);
.LBB0_936:
	v_sub_u32_e64 v144, s68, 8 clamp
	s_mov_b32 s99, 0x60000
	v_mul_lo_u32 v144, v144, s99
	v_mov_b32_e32 v145, v151
	v_lshl_add_u64 v[142:143], s[90:91], 0, v[144:145]
	v_lshl_add_u64 v[140:141], v[166:167], 1, v[142:143]
	v_lshl_add_u64 v[140:141], v[140:141], 0, v[150:151]
	global_load_dwordx4 v[130:133], v[140:141], off
	v_lshl_add_u64 v[140:141], v[168:169], 1, v[142:143]
	v_lshl_add_u64 v[140:141], v[140:141], 0, v[150:151]
	global_load_dwordx4 v[134:137], v[140:141], off
	v_lshl_add_u64 v[142:143], s[92:93], 0, v[144:145]
	v_lshl_add_u64 v[140:141], v[166:167], 1, v[142:143]
	v_lshl_add_u64 v[140:141], v[140:141], 0, v[150:151]
	global_load_dwordx4 v[138:141], v[140:141], off
	v_lshl_add_u64 v[144:145], v[168:169], 1, v[142:143]
	v_lshl_add_u64 v[144:145], v[144:145], 0, v[150:151]
	global_load_dwordx4 v[142:145], v[144:145], off
	v_div_scale_f32 v32, s[0:1], v146, v146, v147
	v_rcp_f32_e32 v34, v32
	v_div_scale_f32 v33, vcc, v147, v146, v147
	v_fma_f32 v35, -v32, v34, 1.0
	v_fmac_f32_e32 v34, v35, v34
	v_mul_f32_e32 v35, v33, v34
	v_fma_f32 v36, -v32, v35, v33
	v_fmac_f32_e32 v35, v36, v34
	v_fma_f32 v32, -v32, v35, v33
	v_div_fmas_f32 v32, v32, v34, v35
	v_div_fixup_f32 v32, v32, v146, v147
	v_cmp_lt_f32_e32 vcc, 0, v146
	s_mov_b32 s0, 0x60000
	v_lshlrev_b64 v[146:147], 1, v[166:167]
	v_cndmask_b32_e32 v32, 0, v32, vcc
	v_lshlrev_b64 v[162:163], 1, v[168:169]
	s_mov_b32 s2, 0
	v_mov_b32_e32 v166, 0
	v_mov_b32_e32 v168, 0xf149f2ca
	v_lshlrev_b32_e32 v34, 16, v220
	v_and_b32_e32 v35, 0xffff0000, v220
	v_lshlrev_b32_e32 v2, 16, v221
	v_and_b32_e32 v3, 0xffff0000, v221
	v_lshlrev_b32_e32 v36, 16, v222
	v_and_b32_e32 v37, 0xffff0000, v222
	v_lshlrev_b32_e32 v4, 16, v223
	v_and_b32_e32 v5, 0xffff0000, v223
	v_lshlrev_b32_e32 v38, 16, v224
	v_and_b32_e32 v39, 0xffff0000, v224
	v_lshlrev_b32_e32 v6, 16, v225
	v_and_b32_e32 v7, 0xffff0000, v225
	v_lshlrev_b32_e32 v40, 16, v226
	v_and_b32_e32 v41, 0xffff0000, v226
	v_lshlrev_b32_e32 v8, 16, v227
	v_and_b32_e32 v9, 0xffff0000, v227
	v_lshlrev_b32_e32 v42, 16, v228
	v_and_b32_e32 v43, 0xffff0000, v228
	v_lshlrev_b32_e32 v10, 16, v229
	v_and_b32_e32 v11, 0xffff0000, v229
	v_lshlrev_b32_e32 v44, 16, v230
	v_and_b32_e32 v45, 0xffff0000, v230
	v_lshlrev_b32_e32 v12, 16, v231
	v_and_b32_e32 v13, 0xffff0000, v231
	v_pk_fma_f32 v[2:3], v[204:205], v[32:33], v[2:3] op_sel_hi:[1,0,1]
	v_pk_fma_f32 v[34:35], v[202:203], v[32:33], v[34:35] op_sel_hi:[1,0,1]
	v_pk_fma_f32 v[4:5], v[200:201], v[32:33], v[4:5] op_sel_hi:[1,0,1]
	v_pk_fma_f32 v[36:37], v[198:199], v[32:33], v[36:37] op_sel_hi:[1,0,1]
	v_pk_fma_f32 v[6:7], v[196:197], v[32:33], v[6:7] op_sel_hi:[1,0,1]
	v_pk_fma_f32 v[38:39], v[194:195], v[32:33], v[38:39] op_sel_hi:[1,0,1]
	v_pk_fma_f32 v[8:9], v[188:189], v[32:33], v[8:9] op_sel_hi:[1,0,1]
	v_pk_fma_f32 v[40:41], v[184:185], v[32:33], v[40:41] op_sel_hi:[1,0,1]
	v_pk_fma_f32 v[10:11], v[192:193], v[32:33], v[10:11] op_sel_hi:[1,0,1]
	v_pk_fma_f32 v[42:43], v[190:191], v[32:33], v[42:43] op_sel_hi:[1,0,1]
	v_pk_fma_f32 v[12:13], v[182:183], v[32:33], v[12:13] op_sel_hi:[1,0,1]
	v_pk_fma_f32 v[44:45], v[180:181], v[32:33], v[44:45] op_sel_hi:[1,0,1]
	v_cvt_pk_bf16_f32 v220, v34, v35
	v_cvt_pk_bf16_f32 v221, v2, v3
	v_cvt_pk_bf16_f32 v222, v36, v37
	v_cvt_pk_bf16_f32 v223, v4, v5
	v_cvt_pk_bf16_f32 v224, v38, v39
	v_cvt_pk_bf16_f32 v225, v6, v7
	v_cvt_pk_bf16_f32 v226, v40, v41
	v_cvt_pk_bf16_f32 v227, v8, v9
	v_cvt_pk_bf16_f32 v228, v42, v43
	v_cvt_pk_bf16_f32 v229, v10, v11
	v_cvt_pk_bf16_f32 v230, v44, v45
	v_cvt_pk_bf16_f32 v231, v12, v13
	v_lshlrev_b32_e32 v2, 16, v232
	v_and_b32_e32 v3, 0xffff0000, v232
	v_lshlrev_b32_e32 v6, 16, v233
	v_and_b32_e32 v7, 0xffff0000, v233
	v_pk_fma_f32 v[6:7], v[178:179], v[32:33], v[6:7] op_sel_hi:[1,0,1]
	v_pk_fma_f32 v[2:3], v[176:177], v[32:33], v[2:3] op_sel_hi:[1,0,1]
	v_sub_u32_e64 v8, s68, 8 clamp
	v_cvt_pk_bf16_f32 v232, v2, v3
	v_cvt_pk_bf16_f32 v233, v6, v7
	v_lshlrev_b32_e32 v2, 16, v234
	v_and_b32_e32 v3, 0xffff0000, v234
	v_lshlrev_b32_e32 v6, 16, v235
	v_and_b32_e32 v7, 0xffff0000, v235
	v_pk_fma_f32 v[6:7], v[174:175], v[32:33], v[6:7] op_sel_hi:[1,0,1]
	v_pk_fma_f32 v[2:3], v[172:173], v[32:33], v[2:3] op_sel_hi:[1,0,1]
	v_mov_b32_e32 v16, v151
	v_cvt_pk_bf16_f32 v234, v2, v3
	v_cvt_pk_bf16_f32 v235, v6, v7
	v_lshlrev_b32_e32 v2, 16, v236
	v_and_b32_e32 v3, 0xffff0000, v236
	v_lshlrev_b32_e32 v6, 16, v237
; __device__ __forceinline__ u32x2 pack4(f32x4 v) { u32x2 w; w.x = cvtpk(v[0], v[1]); w.y = cvtpk(v[2], v[3]); return w; }
; __device__ __forceinline__ void nsa_unit(Frame& F, int b, int g, int c) {
;     ...
;     { const float sc = l > 0.f ? gs / l : 0.f;
; #pragma unroll
;       for (int db = 0; db < 4; ++db)
; #pragma unroll
;           for (int q4 = 0; q4 < 4; ++q4) { bf16_t* p = accb + 32 * db + 8 * q4 + 4 * hi; f32x4 o = {O[db][4 * q4], O[db][4 * q4 + 1], O[db][4 * q4 + 2], O[db][4 * q4 + 3]}; const u32x2 w = *(const u32x2*)p;
;               const f32x4 pr = {__uint_as_float(w.x << 16), __uint_as_float(w.x & 0xffff0000u), __uint_as_float(w.y << 16), __uint_as_float(w.y & 0xffff0000u)}; *(u32x2*)p = pack4(pr + o * sc); } }
;     m = -1e30f; l = 0.f; zero_o(O);
;     run_seq<M_WIN, 8>(lds, tid, qf, O, m, l, C, KV + 4 * 512, 3072, KV, KV + 5 * 512, 3072, c >= 8 ? c - 8 : 0, c, 0ull, ts, ts - 512, 0ull, 0, 0.f, tokl, head);
	v_and_b32_e32 v7, 0xffff0000, v237
	v_pk_fma_f32 v[6:7], v[96:97], v[32:33], v[6:7] op_sel_hi:[1,0,1]
	v_pk_fma_f32 v[2:3], v[94:95], v[32:33], v[2:3] op_sel_hi:[1,0,1]
	v_mov_b32_e32 v17, v151
	v_cvt_pk_bf16_f32 v236, v2, v3
	v_cvt_pk_bf16_f32 v237, v6, v7
	v_lshlrev_b32_e32 v2, 16, v238
	v_and_b32_e32 v3, 0xffff0000, v238
	v_lshlrev_b32_e32 v6, 16, v239
	v_and_b32_e32 v7, 0xffff0000, v239
	v_pk_fma_f32 v[6:7], v[92:93], v[32:33], v[6:7] op_sel_hi:[1,0,1]
	v_pk_fma_f32 v[2:3], v[90:91], v[32:33], v[2:3] op_sel_hi:[1,0,1]
	v_readfirstlane_b32 s3, v8
	v_cvt_pk_bf16_f32 v238, v2, v3
	v_cvt_pk_bf16_f32 v239, v6, v7
	v_lshlrev_b32_e32 v2, 16, v240
	v_and_b32_e32 v3, 0xffff0000, v240
	v_lshlrev_b32_e32 v6, 16, v241
	v_and_b32_e32 v7, 0xffff0000, v241
	v_pk_fma_f32 v[6:7], v[88:89], v[32:33], v[6:7] op_sel_hi:[1,0,1]
	v_pk_fma_f32 v[2:3], v[86:87], v[32:33], v[2:3] op_sel_hi:[1,0,1]
	v_mov_b32_e32 v9, v151
	v_cvt_pk_bf16_f32 v240, v2, v3
	v_cvt_pk_bf16_f32 v241, v6, v7
	v_lshlrev_b32_e32 v2, 16, v242
	v_and_b32_e32 v3, 0xffff0000, v242
	v_lshlrev_b32_e32 v6, 16, v243
	v_and_b32_e32 v7, 0xffff0000, v243
	v_pk_fma_f32 v[6:7], v[84:85], v[32:33], v[6:7] op_sel_hi:[1,0,1]
	v_pk_fma_f32 v[2:3], v[82:83], v[32:33], v[2:3] op_sel_hi:[1,0,1]
	v_mov_b32_e32 v10, v151
	v_cvt_pk_bf16_f32 v242, v2, v3
	v_cvt_pk_bf16_f32 v243, v6, v7
	v_lshlrev_b32_e32 v2, 16, v246
	v_and_b32_e32 v3, 0xffff0000, v246
	v_lshlrev_b32_e32 v6, 16, v247
	v_and_b32_e32 v7, 0xffff0000, v247
	v_pk_fma_f32 v[6:7], v[80:81], v[32:33], v[6:7] op_sel_hi:[1,0,1]
	v_pk_fma_f32 v[2:3], v[78:79], v[32:33], v[2:3] op_sel_hi:[1,0,1]
	v_mov_b32_e32 v11, v151
	v_cvt_pk_bf16_f32 v246, v2, v3
	v_cvt_pk_bf16_f32 v247, v6, v7
	v_lshlrev_b32_e32 v2, 16, v248
	v_and_b32_e32 v3, 0xffff0000, v248
	v_lshlrev_b32_e32 v6, 16, v249
	v_and_b32_e32 v7, 0xffff0000, v249
	v_pk_fma_f32 v[6:7], v[76:77], v[32:33], v[6:7] op_sel_hi:[1,0,1]
	v_pk_fma_f32 v[2:3], v[74:75], v[32:33], v[2:3] op_sel_hi:[1,0,1]
	v_mov_b32_e32 v12, v151
	v_cvt_pk_bf16_f32 v248, v2, v3
	v_cvt_pk_bf16_f32 v249, v6, v7
	v_lshlrev_b32_e32 v2, 16, v250
	v_and_b32_e32 v3, 0xffff0000, v250
	v_lshlrev_b32_e32 v6, 16, v251
	v_and_b32_e32 v7, 0xffff0000, v251
	v_pk_fma_f32 v[6:7], v[72:73], v[32:33], v[6:7] op_sel_hi:[1,0,1]
	v_pk_fma_f32 v[2:3], v[70:71], v[32:33], v[2:3] op_sel_hi:[1,0,1]
	v_mov_b32_e32 v13, v151
	v_cvt_pk_bf16_f32 v250, v2, v3
	v_cvt_pk_bf16_f32 v251, v6, v7
	v_lshlrev_b32_e32 v2, 16, v252
	v_and_b32_e32 v3, 0xffff0000, v252
	v_lshlrev_b32_e32 v4, 16, v253
	v_and_b32_e32 v5, 0xffff0000, v253
	v_pk_fma_f32 v[4:5], v[68:69], v[32:33], v[4:5] op_sel_hi:[1,0,1]
	v_pk_fma_f32 v[2:3], v[66:67], v[32:33], v[2:3] op_sel_hi:[1,0,1]
	v_mov_b32_e32 v14, v151
	v_cvt_pk_bf16_f32 v252, v2, v3
	v_cvt_pk_bf16_f32 v253, v4, v5
	v_mul_lo_u32 v2, v8, s0
	v_mov_b32_e32 v3, v151
	v_lshl_add_u64 v[4:5], s[90:91], 0, v[2:3]
	v_lshl_add_u64 v[6:7], v[4:5], 0, v[146:147]
	v_lshl_add_u64 v[4:5], v[4:5], 0, v[162:163]
	v_lshl_add_u64 v[2:3], s[92:93], 0, v[2:3]
	v_lshl_add_u64 v[6:7], v[6:7], 0, v[150:151]
	v_lshl_add_u64 v[4:5], v[4:5], 0, v[150:151]
	s_barrier
	v_lshl_add_u64 v[4:5], v[2:3], 0, v[146:147]
	v_lshl_add_u64 v[4:5], v[4:5], 0, v[150:151]
	v_lshl_add_u64 v[2:3], v[2:3], 0, v[162:163]
	v_lshl_add_u64 v[2:3], v[2:3], 0, v[150:151]
	s_min_u32 s0, s68, 8
	s_lshl_b32 s0, s0, 6
	s_add_i32 s0, s0, s74
	v_add_u32_e32 v2, s0, v210
	v_sub_u32_e32 v164, v2, v158
	v_mov_b32_e32 v2, v151
	v_mov_b32_e32 v3, v151
	v_mov_b32_e32 v4, v151
	v_mov_b32_e32 v5, v151
	v_mov_b32_e32 v6, v151
	v_mov_b32_e32 v7, v151
	v_mov_b32_e32 v8, v151
	v_mov_b32_e32 v15, v151
	v_mov_b64_e32 v[32:33], v[16:17]
	v_mov_b64_e32 v[48:49], v[16:17]
	v_mov_b64_e32 v[64:65], v[16:17]
	v_mov_b64_e32 v[30:31], v[14:15]
	v_mov_b64_e32 v[28:29], v[12:13]
	v_mov_b64_e32 v[26:27], v[10:11]
	v_mov_b64_e32 v[24:25], v[8:9]
	v_mov_b64_e32 v[22:23], v[6:7]
	v_mov_b64_e32 v[20:21], v[4:5]
	v_mov_b64_e32 v[18:19], v[2:3]
	v_mov_b64_e32 v[46:47], v[14:15]
	v_mov_b64_e32 v[44:45], v[12:13]
	v_mov_b64_e32 v[42:43], v[10:11]
	v_mov_b64_e32 v[40:41], v[8:9]
	v_mov_b64_e32 v[38:39], v[6:7]
	v_mov_b64_e32 v[36:37], v[4:5]
	v_mov_b64_e32 v[34:35], v[2:3]
	v_mov_b64_e32 v[62:63], v[14:15]
	v_mov_b64_e32 v[60:61], v[12:13]
	v_mov_b64_e32 v[58:59], v[10:11]
	v_mov_b64_e32 v[56:57], v[8:9]
	v_mov_b64_e32 v[54:55], v[6:7]
	v_mov_b64_e32 v[52:53], v[4:5]
	v_mov_b64_e32 v[50:51], v[2:3]

; __global__ void __launch_bounds__(512, 2) fwd(Args args) {
	.amdhsa_kernel _Z3fwd4Args
		.amdhsa_group_segment_fixed_size 0
		.amdhsa_private_segment_fixed_size 0
		.amdhsa_kernarg_size 464
		.amdhsa_user_sgpr_count 2
		.amdhsa_user_sgpr_dispatch_ptr 0
		.amdhsa_user_sgpr_queue_ptr 0
		.amdhsa_user_sgpr_kernarg_segment_ptr 1
		.amdhsa_user_sgpr_dispatch_id 0
		.amdhsa_user_sgpr_kernarg_preload_length 0
		.amdhsa_user_sgpr_kernarg_preload_offset 0
		.amdhsa_user_sgpr_private_segment_size 0
		.amdhsa_uses_dynamic_stack 0
		.amdhsa_enable_private_segment 0
		.amdhsa_system_sgpr_workgroup_id_x 1
		.amdhsa_system_sgpr_workgroup_id_y 0
		.amdhsa_system_sgpr_workgroup_id_z 0
		.amdhsa_system_sgpr_workgroup_info 0
		.amdhsa_system_vgpr_workitem_id 0
		.amdhsa_next_free_vgpr 256
		.amdhsa_next_free_sgpr 102
		.amdhsa_accum_offset 256
		.amdhsa_reserve_vcc 1
		.amdhsa_float_round_mode_32 0
		.amdhsa_float_round_mode_16_64 0
		.amdhsa_float_denorm_mode_32 3
		.amdhsa_float_denorm_mode_16_64 3
		.amdhsa_dx10_clamp 1
		.amdhsa_ieee_mode 1
		.amdhsa_fp16_overflow 0
		.amdhsa_tg_split 0
		.amdhsa_exception_fp_ieee_invalid_op 0
		.amdhsa_exception_fp_denorm_src 0
		.amdhsa_exception_fp_ieee_div_zero 0
		.amdhsa_exception_fp_ieee_overflow 0
		.amdhsa_exception_fp_ieee_underflow 0
		.amdhsa_exception_fp_ieee_inexact 0
		.amdhsa_exception_int_div_zero 0
	.end_amdhsa_kernel

; __global__ void __launch_bounds__(512, 2) fwd(Args args) {
amdhsa.kernels:
  - .agpr_count:     0
    .args:
      - .offset:         0
        .size:           208
        .value_kind:     by_value
      - .offset:         208
        .size:           4
        .value_kind:     hidden_block_count_x
      - .offset:         212
        .size:           4
        .value_kind:     hidden_block_count_y
      - .offset:         216
        .size:           4
        .value_kind:     hidden_block_count_z
      - .offset:         220
        .size:           2
        .value_kind:     hidden_group_size_x
      - .offset:         222
        .size:           2
        .value_kind:     hidden_group_size_y
      - .offset:         224
        .size:           2
        .value_kind:     hidden_group_size_z
      - .offset:         226
        .size:           2
        .value_kind:     hidden_remainder_x
      - .offset:         228
        .size:           2
        .value_kind:     hidden_remainder_y
      - .offset:         230
        .size:           2
        .value_kind:     hidden_remainder_z
      - .offset:         248
        .size:           8
        .value_kind:     hidden_global_offset_x
      - .offset:         256
        .size:           8
        .value_kind:     hidden_global_offset_y
      - .offset:         264
        .size:           8
        .value_kind:     hidden_global_offset_z
      - .offset:         272
        .size:           2
        .value_kind:     hidden_grid_dims
      - .offset:         328
        .size:           4
        .value_kind:     hidden_dynamic_lds_size
    .group_segment_fixed_size: 0
    .kernarg_segment_align: 8
    .kernarg_segment_size: 464
    .language:       OpenCL C
    .language_version:
      - 2
      - 0
    .max_flat_workgroup_size: 512
    .name:           _Z3fwd4Args
    .private_segment_fixed_size: 0
    .sgpr_count:     108
    .sgpr_spill_count: 106
    .symbol:         _Z3fwd4Args.kd
    .uniform_work_group_size: 1
    .uses_dynamic_stack: false
    .vgpr_count:     256
    .vgpr_spill_count: 0
    .wavefront_size: 64
